# static s_setprio 1 for waves 4-7 set once before the layer loop
# speedup vs baseline: 1.0081x; 1.0081x over previous
.LBB0_63:
	s_or_b64 exec, exec, s[0:1]
	s_load_dword s1, s[60:61], 0xf8
	s_mul_i32 s0, s11, s10
	s_lshl_b32 s4, s10, 4
	v_mbcnt_lo_u32_b32 v0, -1, 0
	v_mov_b32_e32 v129, 0
	s_waitcnt lgkmcnt(0)
	s_mul_i32 s0, s0, s1
	v_writelane_b32 v252, s0, 3
	s_lshr_b32 s0, s10, 3
	s_lshl_b32 s1, s10, 9
	s_cmpk_lg_i32 s10, 0x100
	v_writelane_b32 v252, s1, 4
	s_cselect_b64 s[6:7], -1, 0
	v_writelane_b32 v252, s6, 5
	s_ashr_i32 s5, s4, 31
	s_movk_i32 s59, 0x110
	v_writelane_b32 v252, s7, 6
	v_writelane_b32 v252, s0, 7
	s_lshl_b32 s0, s0, 5
	v_writelane_b32 v252, s0, 8
	s_lshl_b32 s0, s10, 12
	v_writelane_b32 v252, s0, 9
	s_lshl_b32 s0, s10, 10
	v_writelane_b32 v252, s0, 10
	s_lshl_b32 s6, s10, 3
	v_readlane_b32 s0, v252, 2
	s_lshl_b32 s0, s0, 6
	s_ashr_i32 s7, s6, 31
	v_writelane_b32 v252, s0, 11
	s_mov_b32 s0, 0x358637bd
	v_mov_b64_e32 v[164:165], s[0:1]
	s_mov_b32 s1, 0
	v_writelane_b32 v252, s0, 12
	v_mov_b32_e32 v162, 0x358637bd
	v_mov_b32_e32 v228, s2
	v_writelane_b32 v252, s1, 13
	s_lshl_b64 s[0:1], s[4:5], 12
	v_writelane_b32 v252, s0, 14
	v_mbcnt_hi_u32_b32 v221, -1, v0
	v_mov_b64_e32 v[166:167], 0x800000
	v_writelane_b32 v252, s1, 15
	v_writelane_b32 v252, s4, 16
	s_lshl_b64 s[0:1], s[4:5], 11
	v_mov_b32_e32 v229, 0x41b17218
	v_writelane_b32 v252, s5, 17
	v_writelane_b32 v252, s0, 18
	v_mov_b32_e32 v230, 0x7ff
	v_mov_b32_e32 v231, 0xff
	v_writelane_b32 v252, s1, 19
	s_lshl_b64 s[0:1], s[6:7], 2
	v_writelane_b32 v252, s0, 20
	v_mov_b32_e32 v232, 0xf191accb
	s_mov_b32 s10, 0
	v_writelane_b32 v252, s1, 21
	s_mov_b32 s0, s6
	v_writelane_b32 v252, s0, 22
	s_mov_b64 s[34:35], 0x40000
	s_nop 0
	v_writelane_b32 v252, s1, 23
	s_lshl_b64 s[0:1], s[6:7], 12
	v_writelane_b32 v252, s0, 24
	s_nop 1
	v_writelane_b32 v252, s1, 25
	s_mov_b32 s1, -1
	v_writelane_b32 v252, s0, 26
	s_nop 1
	v_writelane_b32 v252, s1, 27
	v_writelane_b32 v252, s60, 28
	s_nop 1
	v_writelane_b32 v252, s61, 29
	v_readfirstlane_b32 s100, v163
	s_cmp_ge_u32 s100, 0x100
	s_cbranch_scc0 .Lprio_done
	s_setprio 1
.Lprio_done:
	s_branch .LBB0_66
.LBB0_64:
	s_or_b64 exec, exec, s[6:7]
	s_waitcnt vmcnt(0)
